# v41 with snake MFMA order (one operand changes per step)
# speedup vs baseline: 1.0123x; 1.0123x over previous
.LBB0_159:
	s_add_u32 s0, s22, 0xfff80080
	s_addc_u32 s1, s23, -1
	s_add_i32 s51, 0, 0x10000
	s_cmp_eq_u32 s50, 28
	s_cselect_b32 s27, s15, s1
	s_cselect_b32 s26, s46, s0
	v_add_u32_e32 v140, s51, v143
	s_cselect_b32 s25, s13, s49
	s_cselect_b32 s24, s47, s48
	s_add_i32 s0, 0, 0x14000
	ds_read_b128 v[146:149], v140
	ds_read_b128 v[150:153], v140 offset:1024
	ds_read_b128 v[154:157], v140 offset:2048
	ds_read_b128 v[158:161], v140 offset:3072
	v_add_u32_e32 v140, s0, v143
	ds_read_b128 v[162:165], v140
	ds_read_b128 v[166:169], v140 offset:1024
	ds_read_b128 v[170:173], v140 offset:2048
	ds_read_b128 v[174:177], v140 offset:3072
	v_lshl_add_u64 v[140:141], s[22:23], 0, v[136:137]
	s_add_i32 m0, s35, 0xc000
	ds_read_b128 v[178:181], v144
	ds_read_b128 v[182:185], v144 offset:1024
	ds_read_b128 v[192:195], v144 offset:2048
	ds_read_b128 v[196:199], v144 offset:3072
	ds_read_b128 v[200:203], v144 offset:4096
	ds_read_b128 v[204:207], v144 offset:5120
	ds_read_b128 v[208:211], v144 offset:6144
	ds_read_b128 v[212:215], v144 offset:7168
	global_load_lds_dwordx4 v[140:141], off
	v_lshl_add_u64 v[140:141], s[22:23], 0, v[138:139]
	s_add_i32 m0, s35, 0xe000
	s_nop 0
	global_load_lds_dwordx4 v[140:141], off
	s_waitcnt vmcnt(8)
	s_waitcnt lgkmcnt(0)
	s_setprio 1
	s_barrier

	v_mfma_f32_16x16x32_bf16 v[126:129], v[146:149], v[178:181], v[126:129]
	v_mfma_f32_16x16x32_bf16 v[118:121], v[154:157], v[178:181], v[118:121]
	v_mfma_f32_16x16x32_bf16 v[102:105], v[154:157], v[192:195], v[102:105]
	v_mfma_f32_16x16x32_bf16 v[110:113], v[146:149], v[192:195], v[110:113]
	v_mfma_f32_16x16x32_bf16 v[94:97], v[146:149], v[200:203], v[94:97]
	v_mfma_f32_16x16x32_bf16 v[86:89], v[154:157], v[200:203], v[86:89]
	v_mfma_f32_16x16x32_bf16 v[70:73], v[154:157], v[208:211], v[70:73]
	v_mfma_f32_16x16x32_bf16 v[78:81], v[146:149], v[208:211], v[78:81]
	v_mfma_f32_16x16x32_bf16 v[126:129], v[150:153], v[182:185], v[126:129]
	v_mfma_f32_16x16x32_bf16 v[118:121], v[158:161], v[182:185], v[118:121]
	v_mfma_f32_16x16x32_bf16 v[102:105], v[158:161], v[196:199], v[102:105]
	v_mfma_f32_16x16x32_bf16 v[110:113], v[150:153], v[196:199], v[110:113]
	v_mfma_f32_16x16x32_bf16 v[94:97], v[150:153], v[204:207], v[94:97]
	v_mfma_f32_16x16x32_bf16 v[86:89], v[158:161], v[204:207], v[86:89]
	v_mfma_f32_16x16x32_bf16 v[70:73], v[158:161], v[212:215], v[70:73]
	v_mfma_f32_16x16x32_bf16 v[78:81], v[150:153], v[212:215], v[78:81]


	v_mfma_f32_16x16x32_bf16 v[122:125], v[162:165], v[178:181], v[122:125]
	v_mfma_f32_16x16x32_bf16 v[114:117], v[170:173], v[178:181], v[114:117]
	v_mfma_f32_16x16x32_bf16 v[98:101], v[170:173], v[192:195], v[98:101]
	v_mfma_f32_16x16x32_bf16 v[106:109], v[162:165], v[192:195], v[106:109]
	v_mfma_f32_16x16x32_bf16 v[90:93], v[162:165], v[200:203], v[90:93]
	v_mfma_f32_16x16x32_bf16 v[82:85], v[170:173], v[200:203], v[82:85]
	v_mfma_f32_16x16x32_bf16 v[66:69], v[170:173], v[208:211], v[66:69]
	v_mfma_f32_16x16x32_bf16 v[74:77], v[162:165], v[208:211], v[74:77]
	v_mfma_f32_16x16x32_bf16 v[122:125], v[166:169], v[182:185], v[122:125]
	v_mfma_f32_16x16x32_bf16 v[114:117], v[174:177], v[182:185], v[114:117]
	v_mfma_f32_16x16x32_bf16 v[98:101], v[174:177], v[196:199], v[98:101]
	v_mfma_f32_16x16x32_bf16 v[106:109], v[166:169], v[196:199], v[106:109]
	v_mfma_f32_16x16x32_bf16 v[90:93], v[166:169], v[204:207], v[90:93]
	v_mfma_f32_16x16x32_bf16 v[82:85], v[174:177], v[204:207], v[82:85]
	v_mfma_f32_16x16x32_bf16 v[66:69], v[174:177], v[212:215], v[66:69]
	v_mfma_f32_16x16x32_bf16 v[74:77], v[166:169], v[212:215], v[74:77]
	s_barrier
	s_setprio 0
	s_add_i32 s1, s51, s31
	v_lshl_add_u64 v[140:141], s[24:25], 0, v[186:187]
	s_mov_b32 m0, s1
	ds_read_b128 v[178:181], v144 offset:16384
	ds_read_b128 v[182:185], v144 offset:17408
	ds_read_b128 v[192:195], v144 offset:18432
	ds_read_b128 v[196:199], v144 offset:19456
	ds_read_b128 v[200:203], v144 offset:20480
	ds_read_b128 v[204:207], v144 offset:21504
	ds_read_b128 v[208:211], v144 offset:22528
	ds_read_b128 v[212:215], v144 offset:23552
	global_load_lds_dwordx4 v[140:141], off
	s_add_i32 m0, s1, 0x2000
	s_add_u32 s52, s24, 0x80000
	v_lshl_add_u64 v[216:217], s[24:25], 0, v[130:131]
	s_addc_u32 s53, s25, 0
	s_add_i32 s0, s0, s31
	global_load_lds_dwordx4 v[216:217], off
	v_lshl_add_u64 v[218:219], s[52:53], 0, v[186:187]
	s_mov_b32 m0, s0
	v_lshl_add_u64 v[220:221], s[26:27], 0, v[132:133]
	global_load_lds_dwordx4 v[218:219], off
	v_lshl_add_u64 v[218:219], s[52:53], 0, v[130:131]
	s_add_i32 m0, s0, 0x2000
	s_nop 0
	global_load_lds_dwordx4 v[218:219], off
	v_lshl_add_u64 v[218:219], s[26:27], 0, v[134:135]
	s_mov_b32 m0, s35
	s_nop 0
	global_load_lds_dwordx4 v[218:219], off
	s_mov_b32 m0, s36
	s_nop 0
	global_load_lds_dwordx4 v[220:221], off
	s_waitcnt vmcnt(8)
	s_waitcnt lgkmcnt(0)
	s_setprio 1
	s_barrier

	v_mfma_f32_16x16x32_bf16 v[62:65], v[146:149], v[178:181], v[62:65]
	v_mfma_f32_16x16x32_bf16 v[54:57], v[154:157], v[178:181], v[54:57]
	v_mfma_f32_16x16x32_bf16 v[38:41], v[154:157], v[192:195], v[38:41]
	v_mfma_f32_16x16x32_bf16 v[46:49], v[146:149], v[192:195], v[46:49]
	v_mfma_f32_16x16x32_bf16 v[30:33], v[146:149], v[200:203], v[30:33]
	v_mfma_f32_16x16x32_bf16 v[22:25], v[154:157], v[200:203], v[22:25]
	v_mfma_f32_16x16x32_bf16 v[6:9], v[154:157], v[208:211], v[6:9]
	v_mfma_f32_16x16x32_bf16 v[14:17], v[146:149], v[208:211], v[14:17]
	v_mfma_f32_16x16x32_bf16 v[62:65], v[150:153], v[182:185], v[62:65]
	v_mfma_f32_16x16x32_bf16 v[54:57], v[158:161], v[182:185], v[54:57]
	v_mfma_f32_16x16x32_bf16 v[38:41], v[158:161], v[196:199], v[38:41]
	v_mfma_f32_16x16x32_bf16 v[46:49], v[150:153], v[196:199], v[46:49]
	v_mfma_f32_16x16x32_bf16 v[30:33], v[150:153], v[204:207], v[30:33]
	v_mfma_f32_16x16x32_bf16 v[22:25], v[158:161], v[204:207], v[22:25]
	v_mfma_f32_16x16x32_bf16 v[6:9], v[158:161], v[212:215], v[6:9]
	v_mfma_f32_16x16x32_bf16 v[14:17], v[150:153], v[212:215], v[14:17]


	v_mfma_f32_16x16x32_bf16 v[58:61], v[162:165], v[178:181], v[58:61]
	v_mfma_f32_16x16x32_bf16 v[50:53], v[170:173], v[178:181], v[50:53]
	v_mfma_f32_16x16x32_bf16 v[34:37], v[170:173], v[192:195], v[34:37]
	v_mfma_f32_16x16x32_bf16 v[42:45], v[162:165], v[192:195], v[42:45]
	v_mfma_f32_16x16x32_bf16 v[26:29], v[162:165], v[200:203], v[26:29]
	v_mfma_f32_16x16x32_bf16 v[18:21], v[170:173], v[200:203], v[18:21]
	v_mfma_f32_16x16x32_bf16 v[2:5], v[170:173], v[208:211], v[2:5]
	v_mfma_f32_16x16x32_bf16 v[10:13], v[162:165], v[208:211], v[10:13]
	v_mfma_f32_16x16x32_bf16 v[58:61], v[166:169], v[182:185], v[58:61]
	v_mfma_f32_16x16x32_bf16 v[50:53], v[174:177], v[182:185], v[50:53]
	v_mfma_f32_16x16x32_bf16 v[34:37], v[174:177], v[196:199], v[34:37]
	v_mfma_f32_16x16x32_bf16 v[42:45], v[166:169], v[196:199], v[42:45]
	v_mfma_f32_16x16x32_bf16 v[26:29], v[166:169], v[204:207], v[26:29]
	v_mfma_f32_16x16x32_bf16 v[18:21], v[174:177], v[204:207], v[18:21]
	v_mfma_f32_16x16x32_bf16 v[2:5], v[174:177], v[212:215], v[2:5]
	v_mfma_f32_16x16x32_bf16 v[10:13], v[166:169], v[212:215], v[10:13]
	s_barrier
	s_setprio 0
	s_add_i32 s0, 0, 0x18000
	v_add_u32_e32 v145, s0, v143
	s_add_i32 s1, 0, 0x1c000
	ds_read_b128 v[146:149], v145
	ds_read_b128 v[150:153], v145 offset:1024
	ds_read_b128 v[154:157], v145 offset:2048
	ds_read_b128 v[158:161], v145 offset:3072
	v_add_u32_e32 v145, s1, v143
	ds_read_b128 v[162:165], v145
	ds_read_b128 v[166:169], v145 offset:1024
	ds_read_b128 v[170:173], v145 offset:2048
	ds_read_b128 v[174:177], v145 offset:3072
	s_add_u32 s26, s26, 0x80000
	s_addc_u32 s27, s27, 0
	s_mov_b32 m0, s37
	v_lshl_add_u64 v[222:223], s[26:27], 0, v[134:135]
	ds_read_b128 v[178:181], v144 offset:32768
	ds_read_b128 v[182:185], v144 offset:33792
	ds_read_b128 v[192:195], v144 offset:34816
	ds_read_b128 v[196:199], v144 offset:35840
	ds_read_b128 v[200:203], v144 offset:36864
	ds_read_b128 v[204:207], v144 offset:37888
	ds_read_b128 v[208:211], v144 offset:38912
	ds_read_b128 v[212:215], v144 offset:39936
	global_load_lds_dwordx4 v[222:223], off
	v_lshl_add_u64 v[222:223], s[26:27], 0, v[132:133]
	s_mov_b32 m0, s38
	s_nop 0
	global_load_lds_dwordx4 v[222:223], off
	s_waitcnt vmcnt(8)
	s_waitcnt lgkmcnt(0)
	s_setprio 1
	s_barrier

	v_mfma_f32_16x16x32_bf16 v[126:129], v[146:149], v[178:181], v[126:129]
	v_mfma_f32_16x16x32_bf16 v[118:121], v[154:157], v[178:181], v[118:121]
	v_mfma_f32_16x16x32_bf16 v[102:105], v[154:157], v[192:195], v[102:105]
	v_mfma_f32_16x16x32_bf16 v[110:113], v[146:149], v[192:195], v[110:113]
	v_mfma_f32_16x16x32_bf16 v[94:97], v[146:149], v[200:203], v[94:97]
	v_mfma_f32_16x16x32_bf16 v[86:89], v[154:157], v[200:203], v[86:89]
	v_mfma_f32_16x16x32_bf16 v[70:73], v[154:157], v[208:211], v[70:73]
	v_mfma_f32_16x16x32_bf16 v[78:81], v[146:149], v[208:211], v[78:81]
	v_mfma_f32_16x16x32_bf16 v[126:129], v[150:153], v[182:185], v[126:129]
	v_mfma_f32_16x16x32_bf16 v[118:121], v[158:161], v[182:185], v[118:121]
	v_mfma_f32_16x16x32_bf16 v[102:105], v[158:161], v[196:199], v[102:105]
	v_mfma_f32_16x16x32_bf16 v[110:113], v[150:153], v[196:199], v[110:113]
	v_mfma_f32_16x16x32_bf16 v[94:97], v[150:153], v[204:207], v[94:97]
	v_mfma_f32_16x16x32_bf16 v[86:89], v[158:161], v[204:207], v[86:89]
	v_mfma_f32_16x16x32_bf16 v[70:73], v[158:161], v[212:215], v[70:73]
	v_mfma_f32_16x16x32_bf16 v[78:81], v[150:153], v[212:215], v[78:81]


	v_mfma_f32_16x16x32_bf16 v[122:125], v[162:165], v[178:181], v[122:125]
	v_mfma_f32_16x16x32_bf16 v[114:117], v[170:173], v[178:181], v[114:117]
	v_mfma_f32_16x16x32_bf16 v[98:101], v[170:173], v[192:195], v[98:101]
	v_mfma_f32_16x16x32_bf16 v[106:109], v[162:165], v[192:195], v[106:109]
	v_mfma_f32_16x16x32_bf16 v[90:93], v[162:165], v[200:203], v[90:93]
	v_mfma_f32_16x16x32_bf16 v[82:85], v[170:173], v[200:203], v[82:85]
	v_mfma_f32_16x16x32_bf16 v[66:69], v[170:173], v[208:211], v[66:69]
	v_mfma_f32_16x16x32_bf16 v[74:77], v[162:165], v[208:211], v[74:77]
	v_mfma_f32_16x16x32_bf16 v[122:125], v[166:169], v[182:185], v[122:125]
	v_mfma_f32_16x16x32_bf16 v[114:117], v[174:177], v[182:185], v[114:117]
	v_mfma_f32_16x16x32_bf16 v[98:101], v[174:177], v[196:199], v[98:101]
	v_mfma_f32_16x16x32_bf16 v[106:109], v[166:169], v[196:199], v[106:109]
	v_mfma_f32_16x16x32_bf16 v[90:93], v[166:169], v[204:207], v[90:93]
	v_mfma_f32_16x16x32_bf16 v[82:85], v[174:177], v[204:207], v[82:85]
	v_mfma_f32_16x16x32_bf16 v[66:69], v[174:177], v[212:215], v[66:69]
	v_mfma_f32_16x16x32_bf16 v[74:77], v[166:169], v[212:215], v[74:77]
	s_barrier
	s_setprio 0
	s_add_i32 s0, s0, s31
	v_lshl_add_u64 v[140:141], v[140:141], 0, s[84:85]
	s_mov_b32 m0, s0
	ds_read_b128 v[178:181], v144 offset:49152
	ds_read_b128 v[182:185], v144 offset:50176
	ds_read_b128 v[192:195], v144 offset:51200
	ds_read_b128 v[196:199], v144 offset:52224
	ds_read_b128 v[200:203], v144 offset:53248
	ds_read_b128 v[204:207], v144 offset:54272
	ds_read_b128 v[208:211], v144 offset:55296
	ds_read_b128 v[212:215], v144 offset:56320
	global_load_lds_dwordx4 v[140:141], off
	s_add_i32 m0, s0, 0x2000
	s_add_u32 s24, s24, 0x80080
	v_lshl_add_u64 v[140:141], v[216:217], 0, s[84:85]
	s_addc_u32 s25, s25, 0
	s_add_i32 s0, s1, s31
	global_load_lds_dwordx4 v[140:141], off
	v_lshl_add_u64 v[140:141], s[24:25], 0, v[186:187]
	s_mov_b32 m0, s0
	s_nop 0
	global_load_lds_dwordx4 v[140:141], off
	v_lshl_add_u64 v[140:141], s[24:25], 0, v[130:131]
	s_add_i32 m0, s0, 0x2000
	s_nop 0
	global_load_lds_dwordx4 v[140:141], off
	v_lshl_add_u64 v[140:141], v[218:219], 0, s[84:85]
	s_mov_b32 m0, s39
	s_nop 0
	global_load_lds_dwordx4 v[140:141], off
	v_lshl_add_u64 v[140:141], v[220:221], 0, s[84:85]
	s_mov_b32 m0, s40
	s_nop 0
	global_load_lds_dwordx4 v[140:141], off
	s_waitcnt vmcnt(8)
	s_waitcnt lgkmcnt(0)
	s_setprio 1
	s_barrier

	v_mfma_f32_16x16x32_bf16 v[62:65], v[146:149], v[178:181], v[62:65]
	v_mfma_f32_16x16x32_bf16 v[54:57], v[154:157], v[178:181], v[54:57]
	v_mfma_f32_16x16x32_bf16 v[38:41], v[154:157], v[192:195], v[38:41]
	v_mfma_f32_16x16x32_bf16 v[46:49], v[146:149], v[192:195], v[46:49]
	v_mfma_f32_16x16x32_bf16 v[30:33], v[146:149], v[200:203], v[30:33]
	v_mfma_f32_16x16x32_bf16 v[22:25], v[154:157], v[200:203], v[22:25]
	v_mfma_f32_16x16x32_bf16 v[6:9], v[154:157], v[208:211], v[6:9]
	v_mfma_f32_16x16x32_bf16 v[14:17], v[146:149], v[208:211], v[14:17]
	v_mfma_f32_16x16x32_bf16 v[62:65], v[150:153], v[182:185], v[62:65]
	v_mfma_f32_16x16x32_bf16 v[54:57], v[158:161], v[182:185], v[54:57]
	v_mfma_f32_16x16x32_bf16 v[38:41], v[158:161], v[196:199], v[38:41]
	v_mfma_f32_16x16x32_bf16 v[46:49], v[150:153], v[196:199], v[46:49]
	v_mfma_f32_16x16x32_bf16 v[30:33], v[150:153], v[204:207], v[30:33]
	v_mfma_f32_16x16x32_bf16 v[22:25], v[158:161], v[204:207], v[22:25]
	v_mfma_f32_16x16x32_bf16 v[6:9], v[158:161], v[212:215], v[6:9]
	v_mfma_f32_16x16x32_bf16 v[14:17], v[150:153], v[212:215], v[14:17]


	v_mfma_f32_16x16x32_bf16 v[58:61], v[162:165], v[178:181], v[58:61]
	v_mfma_f32_16x16x32_bf16 v[50:53], v[170:173], v[178:181], v[50:53]
	v_mfma_f32_16x16x32_bf16 v[34:37], v[170:173], v[192:195], v[34:37]
	v_mfma_f32_16x16x32_bf16 v[42:45], v[162:165], v[192:195], v[42:45]
	v_mfma_f32_16x16x32_bf16 v[26:29], v[162:165], v[200:203], v[26:29]
	v_mfma_f32_16x16x32_bf16 v[18:21], v[170:173], v[200:203], v[18:21]
	v_mfma_f32_16x16x32_bf16 v[2:5], v[170:173], v[208:211], v[2:5]
	v_mfma_f32_16x16x32_bf16 v[10:13], v[162:165], v[208:211], v[10:13]
	v_mfma_f32_16x16x32_bf16 v[58:61], v[166:169], v[182:185], v[58:61]
	v_mfma_f32_16x16x32_bf16 v[50:53], v[174:177], v[182:185], v[50:53]
	v_mfma_f32_16x16x32_bf16 v[34:37], v[174:177], v[196:199], v[34:37]
	v_mfma_f32_16x16x32_bf16 v[42:45], v[166:169], v[196:199], v[42:45]
	v_mfma_f32_16x16x32_bf16 v[26:29], v[166:169], v[204:207], v[26:29]
	v_mfma_f32_16x16x32_bf16 v[18:21], v[174:177], v[204:207], v[18:21]
	v_mfma_f32_16x16x32_bf16 v[2:5], v[174:177], v[212:215], v[2:5]
	v_mfma_f32_16x16x32_bf16 v[10:13], v[166:169], v[212:215], v[10:13]
	s_barrier
	s_setprio 0
	s_add_i32 s50, s50, 2
	s_add_u32 s22, s22, 0x100
	s_addc_u32 s23, s23, 0
	s_add_u32 s48, s48, 0x100
	s_addc_u32 s49, s49, 0
	s_cmp_gt_u32 s50, 29
	s_cbranch_scc0 .LBB0_159
	s_and_b64 vcc, exec, s[10:11]
	s_cbranch_vccz .LBB0_162
	s_barrier

.LBB0_243:
	s_add_u32 s22, s20, 0x100
	s_addc_u32 s23, s21, 0
	s_add_i32 s0, 0, 0x10000
	s_cmpk_eq_i32 s51, 0x54
	s_cselect_b32 s27, s7, s23
	s_cselect_b32 s26, s6, s22
	s_cselect_b32 s25, s19, s50
	s_cselect_b32 s24, s18, s49
	s_add_i32 s1, 0, 0x14000
	v_add_u32_e32 v126, s0, v237
	v_add_u32_e32 v158, s1, v237
	ds_read_b128 v[90:93], v126
	ds_read_b128 v[102:105], v126 offset:1024
	ds_read_b128 v[114:117], v126 offset:2048
	ds_read_b128 v[126:129], v126 offset:3072
	ds_read_b128 v[138:141], v158
	ds_read_b128 v[142:145], v158 offset:1024
	ds_read_b128 v[154:157], v158 offset:2048
	ds_read_b128 v[158:161], v158 offset:3072
	v_lshl_add_u64 v[210:211], s[20:21], 0, v[198:199]
	s_add_i32 m0, s34, 0xc000
	ds_read_b128 v[162:165], v238
	ds_read_b128 v[166:169], v238 offset:1024
	ds_read_b128 v[170:173], v238 offset:2048
	ds_read_b128 v[174:177], v238 offset:3072
	ds_read_b128 v[178:181], v238 offset:4096
	ds_read_b128 v[182:185], v238 offset:5120
	ds_read_b128 v[202:205], v238 offset:6144
	ds_read_b128 v[206:209], v238 offset:7168
	global_load_lds_dwordx4 v[210:211], off
	v_lshl_add_u64 v[210:211], s[20:21], 0, v[200:201]
	s_add_i32 m0, s34, 0xe000
	s_nop 0
	global_load_lds_dwordx4 v[210:211], off
	s_waitcnt vmcnt(8)
	s_waitcnt lgkmcnt(0)
	s_setprio 1
	s_barrier

	v_mfma_f32_16x16x32_bf16 v[150:153], v[90:93], v[162:165], v[150:153]
	v_mfma_f32_16x16x32_bf16 v[146:149], v[114:117], v[162:165], v[146:149]
	v_mfma_f32_16x16x32_bf16 v[118:121], v[114:117], v[170:173], v[118:121]
	v_mfma_f32_16x16x32_bf16 v[122:125], v[90:93], v[170:173], v[122:125]
	v_mfma_f32_16x16x32_bf16 v[98:101], v[90:93], v[178:181], v[98:101]
	v_mfma_f32_16x16x32_bf16 v[94:97], v[114:117], v[178:181], v[94:97]
	v_mfma_f32_16x16x32_bf16 v[74:77], v[114:117], v[202:205], v[74:77]
	v_mfma_f32_16x16x32_bf16 v[78:81], v[90:93], v[202:205], v[78:81]
	v_mfma_f32_16x16x32_bf16 v[150:153], v[102:105], v[166:169], v[150:153]
	v_mfma_f32_16x16x32_bf16 v[146:149], v[126:129], v[166:169], v[146:149]
	v_mfma_f32_16x16x32_bf16 v[118:121], v[126:129], v[174:177], v[118:121]
	v_mfma_f32_16x16x32_bf16 v[122:125], v[102:105], v[174:177], v[122:125]
	v_mfma_f32_16x16x32_bf16 v[98:101], v[102:105], v[182:185], v[98:101]
	v_mfma_f32_16x16x32_bf16 v[94:97], v[126:129], v[182:185], v[94:97]
	v_mfma_f32_16x16x32_bf16 v[74:77], v[126:129], v[206:209], v[74:77]
	v_mfma_f32_16x16x32_bf16 v[78:81], v[102:105], v[206:209], v[78:81]


	v_mfma_f32_16x16x32_bf16 v[134:137], v[138:141], v[162:165], v[134:137]
	v_mfma_f32_16x16x32_bf16 v[130:133], v[154:157], v[162:165], v[130:133]
	v_mfma_f32_16x16x32_bf16 v[106:109], v[154:157], v[170:173], v[106:109]
	v_mfma_f32_16x16x32_bf16 v[110:113], v[138:141], v[170:173], v[110:113]
	v_mfma_f32_16x16x32_bf16 v[86:89], v[138:141], v[178:181], v[86:89]
	v_mfma_f32_16x16x32_bf16 v[82:85], v[154:157], v[178:181], v[82:85]
	v_mfma_f32_16x16x32_bf16 v[66:69], v[154:157], v[202:205], v[66:69]
	v_mfma_f32_16x16x32_bf16 v[70:73], v[138:141], v[202:205], v[70:73]
	v_mfma_f32_16x16x32_bf16 v[134:137], v[142:145], v[166:169], v[134:137]
	v_mfma_f32_16x16x32_bf16 v[130:133], v[158:161], v[166:169], v[130:133]
	v_mfma_f32_16x16x32_bf16 v[106:109], v[158:161], v[174:177], v[106:109]
	v_mfma_f32_16x16x32_bf16 v[110:113], v[142:145], v[174:177], v[110:113]
	v_mfma_f32_16x16x32_bf16 v[86:89], v[142:145], v[182:185], v[86:89]
	v_mfma_f32_16x16x32_bf16 v[82:85], v[158:161], v[182:185], v[82:85]
	v_mfma_f32_16x16x32_bf16 v[66:69], v[158:161], v[206:209], v[66:69]
	v_mfma_f32_16x16x32_bf16 v[70:73], v[142:145], v[206:209], v[70:73]
	s_barrier
	s_setprio 0
	s_add_i32 s0, s0, s31
	v_lshl_add_u64 v[210:211], s[24:25], 0, v[186:187]
	s_mov_b32 m0, s0
	ds_read_b128 v[162:165], v238 offset:16384
	ds_read_b128 v[166:169], v238 offset:17408
	ds_read_b128 v[170:173], v238 offset:18432
	ds_read_b128 v[174:177], v238 offset:19456
	ds_read_b128 v[178:181], v238 offset:20480
	ds_read_b128 v[182:185], v238 offset:21504
	ds_read_b128 v[202:205], v238 offset:22528
	ds_read_b128 v[206:209], v238 offset:23552
	global_load_lds_dwordx4 v[210:211], off
	s_add_i32 m0, s0, 0x2000
	s_add_u32 s20, s24, 0x160000
	v_lshl_add_u64 v[212:213], s[24:25], 0, v[196:197]
	s_addc_u32 s21, s25, 0
	s_add_i32 s0, s1, s31
	global_load_lds_dwordx4 v[212:213], off
	v_lshl_add_u64 v[214:215], s[20:21], 0, v[186:187]
	s_mov_b32 m0, s0
	v_lshl_add_u64 v[216:217], s[26:27], 0, v[194:195]
	global_load_lds_dwordx4 v[214:215], off
	v_lshl_add_u64 v[214:215], s[20:21], 0, v[196:197]
	s_add_i32 m0, s0, 0x2000
	s_nop 0
	global_load_lds_dwordx4 v[214:215], off
	v_lshl_add_u64 v[214:215], s[26:27], 0, v[192:193]
	s_mov_b32 m0, s34
	s_nop 0
	global_load_lds_dwordx4 v[214:215], off
	s_mov_b32 m0, s35
	s_nop 0
	global_load_lds_dwordx4 v[216:217], off
	s_waitcnt vmcnt(8)
	s_waitcnt lgkmcnt(0)
	s_setprio 1
	s_barrier

	v_mfma_f32_16x16x32_bf16 v[62:65], v[90:93], v[162:165], v[62:65]
	v_mfma_f32_16x16x32_bf16 v[58:61], v[114:117], v[162:165], v[58:61]
	v_mfma_f32_16x16x32_bf16 v[42:45], v[114:117], v[170:173], v[42:45]
	v_mfma_f32_16x16x32_bf16 v[46:49], v[90:93], v[170:173], v[46:49]
	v_mfma_f32_16x16x32_bf16 v[30:33], v[90:93], v[178:181], v[30:33]
	v_mfma_f32_16x16x32_bf16 v[26:29], v[114:117], v[178:181], v[26:29]
	v_mfma_f32_16x16x32_bf16 v[10:13], v[114:117], v[202:205], v[10:13]
	v_mfma_f32_16x16x32_bf16 v[14:17], v[90:93], v[202:205], v[14:17]
	v_mfma_f32_16x16x32_bf16 v[62:65], v[102:105], v[166:169], v[62:65]
	v_mfma_f32_16x16x32_bf16 v[58:61], v[126:129], v[166:169], v[58:61]
	v_mfma_f32_16x16x32_bf16 v[42:45], v[126:129], v[174:177], v[42:45]
	v_mfma_f32_16x16x32_bf16 v[46:49], v[102:105], v[174:177], v[46:49]
	v_mfma_f32_16x16x32_bf16 v[30:33], v[102:105], v[182:185], v[30:33]
	v_mfma_f32_16x16x32_bf16 v[26:29], v[126:129], v[182:185], v[26:29]
	v_mfma_f32_16x16x32_bf16 v[10:13], v[126:129], v[206:209], v[10:13]
	v_mfma_f32_16x16x32_bf16 v[14:17], v[102:105], v[206:209], v[14:17]


	v_mfma_f32_16x16x32_bf16 v[54:57], v[138:141], v[162:165], v[54:57]
	v_mfma_f32_16x16x32_bf16 v[50:53], v[154:157], v[162:165], v[50:53]
	v_mfma_f32_16x16x32_bf16 v[34:37], v[154:157], v[170:173], v[34:37]
	v_mfma_f32_16x16x32_bf16 v[38:41], v[138:141], v[170:173], v[38:41]
	v_mfma_f32_16x16x32_bf16 v[22:25], v[138:141], v[178:181], v[22:25]
	v_mfma_f32_16x16x32_bf16 v[18:21], v[154:157], v[178:181], v[18:21]
	v_mfma_f32_16x16x32_bf16 v[2:5], v[154:157], v[202:205], v[2:5]
	v_mfma_f32_16x16x32_bf16 v[6:9], v[138:141], v[202:205], v[6:9]
	v_mfma_f32_16x16x32_bf16 v[54:57], v[142:145], v[166:169], v[54:57]
	v_mfma_f32_16x16x32_bf16 v[50:53], v[158:161], v[166:169], v[50:53]
	v_mfma_f32_16x16x32_bf16 v[34:37], v[158:161], v[174:177], v[34:37]
	v_mfma_f32_16x16x32_bf16 v[38:41], v[142:145], v[174:177], v[38:41]
	v_mfma_f32_16x16x32_bf16 v[22:25], v[142:145], v[182:185], v[22:25]
	v_mfma_f32_16x16x32_bf16 v[18:21], v[158:161], v[182:185], v[18:21]
	v_mfma_f32_16x16x32_bf16 v[2:5], v[158:161], v[206:209], v[2:5]
	v_mfma_f32_16x16x32_bf16 v[6:9], v[142:145], v[206:209], v[6:9]
	s_barrier
	s_setprio 0
	s_add_i32 s0, 0, 0x18000
	s_add_i32 s1, 0, 0x1c000
	v_add_u32_e32 v126, s0, v237
	v_add_u32_e32 v158, s1, v237
	ds_read_b128 v[90:93], v126
	ds_read_b128 v[102:105], v126 offset:1024
	ds_read_b128 v[114:117], v126 offset:2048
	ds_read_b128 v[126:129], v126 offset:3072
	ds_read_b128 v[138:141], v158
	ds_read_b128 v[142:145], v158 offset:1024
	ds_read_b128 v[154:157], v158 offset:2048
	ds_read_b128 v[158:161], v158 offset:3072
	s_add_u32 s20, s26, 0x160000
	s_addc_u32 s21, s27, 0
	s_mov_b32 m0, s36
	v_lshl_add_u64 v[218:219], s[20:21], 0, v[192:193]
	ds_read_b128 v[162:165], v238 offset:32768
	ds_read_b128 v[166:169], v238 offset:33792
	ds_read_b128 v[170:173], v238 offset:34816
	ds_read_b128 v[174:177], v238 offset:35840
	ds_read_b128 v[178:181], v238 offset:36864
	ds_read_b128 v[182:185], v238 offset:37888
	ds_read_b128 v[202:205], v238 offset:38912
	ds_read_b128 v[206:209], v238 offset:39936
	global_load_lds_dwordx4 v[218:219], off
	v_lshl_add_u64 v[218:219], s[20:21], 0, v[194:195]
	s_mov_b32 m0, s37
	s_nop 0
	global_load_lds_dwordx4 v[218:219], off
	s_waitcnt vmcnt(8)
	s_waitcnt lgkmcnt(0)
	s_setprio 1
	s_barrier

	v_mfma_f32_16x16x32_bf16 v[150:153], v[90:93], v[162:165], v[150:153]
	v_mfma_f32_16x16x32_bf16 v[146:149], v[114:117], v[162:165], v[146:149]
	v_mfma_f32_16x16x32_bf16 v[118:121], v[114:117], v[170:173], v[118:121]
	v_mfma_f32_16x16x32_bf16 v[122:125], v[90:93], v[170:173], v[122:125]
	v_mfma_f32_16x16x32_bf16 v[98:101], v[90:93], v[178:181], v[98:101]
	v_mfma_f32_16x16x32_bf16 v[94:97], v[114:117], v[178:181], v[94:97]
	v_mfma_f32_16x16x32_bf16 v[74:77], v[114:117], v[202:205], v[74:77]
	v_mfma_f32_16x16x32_bf16 v[78:81], v[90:93], v[202:205], v[78:81]
	v_mfma_f32_16x16x32_bf16 v[150:153], v[102:105], v[166:169], v[150:153]
	v_mfma_f32_16x16x32_bf16 v[146:149], v[126:129], v[166:169], v[146:149]
	v_mfma_f32_16x16x32_bf16 v[118:121], v[126:129], v[174:177], v[118:121]
	v_mfma_f32_16x16x32_bf16 v[122:125], v[102:105], v[174:177], v[122:125]
	v_mfma_f32_16x16x32_bf16 v[98:101], v[102:105], v[182:185], v[98:101]
	v_mfma_f32_16x16x32_bf16 v[94:97], v[126:129], v[182:185], v[94:97]
	v_mfma_f32_16x16x32_bf16 v[74:77], v[126:129], v[206:209], v[74:77]
	v_mfma_f32_16x16x32_bf16 v[78:81], v[102:105], v[206:209], v[78:81]


	v_mfma_f32_16x16x32_bf16 v[134:137], v[138:141], v[162:165], v[134:137]
	v_mfma_f32_16x16x32_bf16 v[130:133], v[154:157], v[162:165], v[130:133]
	v_mfma_f32_16x16x32_bf16 v[106:109], v[154:157], v[170:173], v[106:109]
	v_mfma_f32_16x16x32_bf16 v[110:113], v[138:141], v[170:173], v[110:113]
	v_mfma_f32_16x16x32_bf16 v[86:89], v[138:141], v[178:181], v[86:89]
	v_mfma_f32_16x16x32_bf16 v[82:85], v[154:157], v[178:181], v[82:85]
	v_mfma_f32_16x16x32_bf16 v[66:69], v[154:157], v[202:205], v[66:69]
	v_mfma_f32_16x16x32_bf16 v[70:73], v[138:141], v[202:205], v[70:73]
	v_mfma_f32_16x16x32_bf16 v[134:137], v[142:145], v[166:169], v[134:137]
	v_mfma_f32_16x16x32_bf16 v[130:133], v[158:161], v[166:169], v[130:133]
	v_mfma_f32_16x16x32_bf16 v[106:109], v[158:161], v[174:177], v[106:109]
	v_mfma_f32_16x16x32_bf16 v[110:113], v[142:145], v[174:177], v[110:113]
	v_mfma_f32_16x16x32_bf16 v[86:89], v[142:145], v[182:185], v[86:89]
	v_mfma_f32_16x16x32_bf16 v[82:85], v[158:161], v[182:185], v[82:85]
	v_mfma_f32_16x16x32_bf16 v[66:69], v[158:161], v[206:209], v[66:69]
	v_mfma_f32_16x16x32_bf16 v[70:73], v[142:145], v[206:209], v[70:73]
	s_barrier
	s_setprio 0
	s_add_i32 s0, s0, s31
	v_lshl_add_u64 v[210:211], v[210:211], 0, s[84:85]
	s_mov_b32 m0, s0
	ds_read_b128 v[162:165], v238 offset:49152
	ds_read_b128 v[166:169], v238 offset:50176
	ds_read_b128 v[170:173], v238 offset:51200
	ds_read_b128 v[174:177], v238 offset:52224
	ds_read_b128 v[178:181], v238 offset:53248
	ds_read_b128 v[182:185], v238 offset:54272
	ds_read_b128 v[202:205], v238 offset:55296
	ds_read_b128 v[206:209], v238 offset:56320
	global_load_lds_dwordx4 v[210:211], off
	s_add_i32 m0, s0, 0x2000
	s_add_u32 s20, s24, 0x160080
	v_lshl_add_u64 v[210:211], v[212:213], 0, s[84:85]
	s_addc_u32 s21, s25, 0
	s_add_i32 s0, s1, s31
	global_load_lds_dwordx4 v[210:211], off
	v_lshl_add_u64 v[210:211], s[20:21], 0, v[186:187]
	s_mov_b32 m0, s0
	s_nop 0
	global_load_lds_dwordx4 v[210:211], off
	v_lshl_add_u64 v[210:211], s[20:21], 0, v[196:197]
	s_add_i32 m0, s0, 0x2000
	s_nop 0
	global_load_lds_dwordx4 v[210:211], off
	v_lshl_add_u64 v[210:211], v[214:215], 0, s[84:85]
	s_mov_b32 m0, s41
	s_nop 0
	global_load_lds_dwordx4 v[210:211], off
	v_lshl_add_u64 v[210:211], v[216:217], 0, s[84:85]
	s_mov_b32 m0, s42
	s_nop 0
	global_load_lds_dwordx4 v[210:211], off
	s_waitcnt vmcnt(8)
	s_waitcnt lgkmcnt(0)
	s_setprio 1
	s_barrier

	v_mfma_f32_16x16x32_bf16 v[62:65], v[90:93], v[162:165], v[62:65]
	v_mfma_f32_16x16x32_bf16 v[58:61], v[114:117], v[162:165], v[58:61]
	v_mfma_f32_16x16x32_bf16 v[42:45], v[114:117], v[170:173], v[42:45]
	v_mfma_f32_16x16x32_bf16 v[46:49], v[90:93], v[170:173], v[46:49]
	v_mfma_f32_16x16x32_bf16 v[30:33], v[90:93], v[178:181], v[30:33]
	v_mfma_f32_16x16x32_bf16 v[26:29], v[114:117], v[178:181], v[26:29]
	v_mfma_f32_16x16x32_bf16 v[10:13], v[114:117], v[202:205], v[10:13]
	v_mfma_f32_16x16x32_bf16 v[14:17], v[90:93], v[202:205], v[14:17]
	v_mfma_f32_16x16x32_bf16 v[62:65], v[102:105], v[166:169], v[62:65]
	v_mfma_f32_16x16x32_bf16 v[58:61], v[126:129], v[166:169], v[58:61]
	v_mfma_f32_16x16x32_bf16 v[42:45], v[126:129], v[174:177], v[42:45]
	v_mfma_f32_16x16x32_bf16 v[46:49], v[102:105], v[174:177], v[46:49]
	v_mfma_f32_16x16x32_bf16 v[30:33], v[102:105], v[182:185], v[30:33]
	v_mfma_f32_16x16x32_bf16 v[26:29], v[126:129], v[182:185], v[26:29]
	v_mfma_f32_16x16x32_bf16 v[10:13], v[126:129], v[206:209], v[10:13]
	v_mfma_f32_16x16x32_bf16 v[14:17], v[102:105], v[206:209], v[14:17]


	v_mfma_f32_16x16x32_bf16 v[54:57], v[138:141], v[162:165], v[54:57]
	v_mfma_f32_16x16x32_bf16 v[50:53], v[154:157], v[162:165], v[50:53]
	v_mfma_f32_16x16x32_bf16 v[34:37], v[154:157], v[170:173], v[34:37]
	v_mfma_f32_16x16x32_bf16 v[38:41], v[138:141], v[170:173], v[38:41]
	v_mfma_f32_16x16x32_bf16 v[22:25], v[138:141], v[178:181], v[22:25]
	v_mfma_f32_16x16x32_bf16 v[18:21], v[154:157], v[178:181], v[18:21]
	v_mfma_f32_16x16x32_bf16 v[2:5], v[154:157], v[202:205], v[2:5]
	v_mfma_f32_16x16x32_bf16 v[6:9], v[138:141], v[202:205], v[6:9]
	v_mfma_f32_16x16x32_bf16 v[54:57], v[142:145], v[166:169], v[54:57]
	v_mfma_f32_16x16x32_bf16 v[50:53], v[158:161], v[166:169], v[50:53]
	v_mfma_f32_16x16x32_bf16 v[34:37], v[158:161], v[174:177], v[34:37]
	v_mfma_f32_16x16x32_bf16 v[38:41], v[142:145], v[174:177], v[38:41]
	v_mfma_f32_16x16x32_bf16 v[22:25], v[142:145], v[182:185], v[22:25]
	v_mfma_f32_16x16x32_bf16 v[18:21], v[158:161], v[182:185], v[18:21]
	v_mfma_f32_16x16x32_bf16 v[2:5], v[158:161], v[206:209], v[2:5]
	v_mfma_f32_16x16x32_bf16 v[6:9], v[142:145], v[206:209], v[6:9]
	s_barrier
	s_setprio 0
	s_add_i32 s51, s51, 2
	s_add_u32 s49, s49, 0x100
	s_addc_u32 s50, s50, 0
	s_cmpk_gt_u32 s51, 0x55
	s_mov_b64 s[20:21], s[22:23]
	s_cbranch_scc0 .LBB0_243
	s_and_b64 vcc, exec, s[16:17]
	s_cbranch_vccz .LBB0_246
	s_barrier

.LBB0_443:
	s_add_u32 s0, s26, 0xfff80080
	s_addc_u32 s1, s27, -1
	s_add_i32 s56, 0, 0x10000
	s_cmp_eq_u32 s55, 28
	s_cselect_b32 s31, s19, s1
	s_cselect_b32 s30, s51, s0
	v_add_u32_e32 v140, s56, v144
	s_cselect_b32 s29, s17, s54
	s_cselect_b32 s28, s52, s53
	s_add_i32 s0, 0, 0x14000
	ds_read_b128 v[146:149], v140
	ds_read_b128 v[150:153], v140 offset:1024
	ds_read_b128 v[154:157], v140 offset:2048
	ds_read_b128 v[158:161], v140 offset:3072
	v_add_u32_e32 v140, s0, v144
	ds_read_b128 v[162:165], v140
	ds_read_b128 v[166:169], v140 offset:1024
	ds_read_b128 v[170:173], v140 offset:2048
	ds_read_b128 v[174:177], v140 offset:3072
	v_lshl_add_u64 v[140:141], s[26:27], 0, v[136:137]
	s_add_i32 m0, s25, 0xc000
	ds_read_b128 v[178:181], v145
	ds_read_b128 v[182:185], v145 offset:1024
	ds_read_b128 v[192:195], v145 offset:2048
	ds_read_b128 v[196:199], v145 offset:3072
	ds_read_b128 v[200:203], v145 offset:4096
	ds_read_b128 v[204:207], v145 offset:5120
	ds_read_b128 v[208:211], v145 offset:6144
	ds_read_b128 v[212:215], v145 offset:7168
	global_load_lds_dwordx4 v[140:141], off
	v_lshl_add_u64 v[140:141], s[26:27], 0, v[138:139]
	s_add_i32 m0, s25, 0xe000
	s_nop 0
	global_load_lds_dwordx4 v[140:141], off
	s_waitcnt vmcnt(8)
	s_waitcnt lgkmcnt(0)
	s_setprio 1
	s_barrier

	v_mfma_f32_16x16x32_bf16 v[126:129], v[146:149], v[178:181], v[126:129]
	v_mfma_f32_16x16x32_bf16 v[122:125], v[154:157], v[178:181], v[122:125]
	v_mfma_f32_16x16x32_bf16 v[106:109], v[154:157], v[192:195], v[106:109]
	v_mfma_f32_16x16x32_bf16 v[114:117], v[146:149], v[192:195], v[114:117]
	v_mfma_f32_16x16x32_bf16 v[98:101], v[146:149], v[200:203], v[98:101]
	v_mfma_f32_16x16x32_bf16 v[90:93], v[154:157], v[200:203], v[90:93]
	v_mfma_f32_16x16x32_bf16 v[74:77], v[154:157], v[208:211], v[74:77]
	v_mfma_f32_16x16x32_bf16 v[82:85], v[146:149], v[208:211], v[82:85]
	v_mfma_f32_16x16x32_bf16 v[126:129], v[150:153], v[182:185], v[126:129]
	v_mfma_f32_16x16x32_bf16 v[122:125], v[158:161], v[182:185], v[122:125]
	v_mfma_f32_16x16x32_bf16 v[106:109], v[158:161], v[196:199], v[106:109]
	v_mfma_f32_16x16x32_bf16 v[114:117], v[150:153], v[196:199], v[114:117]
	v_mfma_f32_16x16x32_bf16 v[98:101], v[150:153], v[204:207], v[98:101]
	v_mfma_f32_16x16x32_bf16 v[90:93], v[158:161], v[204:207], v[90:93]
	v_mfma_f32_16x16x32_bf16 v[74:77], v[158:161], v[212:215], v[74:77]
	v_mfma_f32_16x16x32_bf16 v[82:85], v[150:153], v[212:215], v[82:85]


	v_mfma_f32_16x16x32_bf16 v[118:121], v[162:165], v[178:181], v[118:121]
	v_mfma_f32_16x16x32_bf16 v[110:113], v[170:173], v[178:181], v[110:113]
	v_mfma_f32_16x16x32_bf16 v[94:97], v[170:173], v[192:195], v[94:97]
	v_mfma_f32_16x16x32_bf16 v[102:105], v[162:165], v[192:195], v[102:105]
	v_mfma_f32_16x16x32_bf16 v[86:89], v[162:165], v[200:203], v[86:89]
	v_mfma_f32_16x16x32_bf16 v[78:81], v[170:173], v[200:203], v[78:81]
	v_mfma_f32_16x16x32_bf16 v[66:69], v[170:173], v[208:211], v[66:69]
	v_mfma_f32_16x16x32_bf16 v[70:73], v[162:165], v[208:211], v[70:73]
	v_mfma_f32_16x16x32_bf16 v[118:121], v[166:169], v[182:185], v[118:121]
	v_mfma_f32_16x16x32_bf16 v[110:113], v[174:177], v[182:185], v[110:113]
	v_mfma_f32_16x16x32_bf16 v[94:97], v[174:177], v[196:199], v[94:97]
	v_mfma_f32_16x16x32_bf16 v[102:105], v[166:169], v[196:199], v[102:105]
	v_mfma_f32_16x16x32_bf16 v[86:89], v[166:169], v[204:207], v[86:89]
	v_mfma_f32_16x16x32_bf16 v[78:81], v[174:177], v[204:207], v[78:81]
	v_mfma_f32_16x16x32_bf16 v[66:69], v[174:177], v[212:215], v[66:69]
	v_mfma_f32_16x16x32_bf16 v[70:73], v[166:169], v[212:215], v[70:73]
	s_barrier
	s_setprio 0
	s_add_i32 s1, s56, s39
	v_lshl_add_u64 v[140:141], s[28:29], 0, v[186:187]
	s_mov_b32 m0, s1
	ds_read_b128 v[178:181], v145 offset:16384
	ds_read_b128 v[182:185], v145 offset:17408
	ds_read_b128 v[192:195], v145 offset:18432
	ds_read_b128 v[196:199], v145 offset:19456
	ds_read_b128 v[200:203], v145 offset:20480
	ds_read_b128 v[204:207], v145 offset:21504
	ds_read_b128 v[208:211], v145 offset:22528
	ds_read_b128 v[212:215], v145 offset:23552
	global_load_lds_dwordx4 v[140:141], off
	s_add_i32 m0, s1, 0x2000
	s_add_u32 s56, s28, 0x80000
	v_lshl_add_u64 v[188:189], s[28:29], 0, v[130:131]
	s_addc_u32 s57, s29, 0
	s_add_i32 s0, s0, s39
	global_load_lds_dwordx4 v[188:189], off
	v_lshl_add_u64 v[216:217], s[56:57], 0, v[186:187]
	s_mov_b32 m0, s0
	v_lshl_add_u64 v[218:219], s[30:31], 0, v[132:133]
	global_load_lds_dwordx4 v[216:217], off
	v_lshl_add_u64 v[216:217], s[56:57], 0, v[130:131]
	s_add_i32 m0, s0, 0x2000
	s_nop 0
	global_load_lds_dwordx4 v[216:217], off
	v_lshl_add_u64 v[216:217], s[30:31], 0, v[134:135]
	s_mov_b32 m0, s25
	s_nop 0
	global_load_lds_dwordx4 v[216:217], off
	s_mov_b32 m0, s40
	s_nop 0
	global_load_lds_dwordx4 v[218:219], off
	s_waitcnt vmcnt(8)
	s_waitcnt lgkmcnt(0)
	s_setprio 1
	s_barrier

	v_mfma_f32_16x16x32_bf16 v[62:65], v[146:149], v[178:181], v[62:65]
	v_mfma_f32_16x16x32_bf16 v[58:61], v[154:157], v[178:181], v[58:61]
	v_mfma_f32_16x16x32_bf16 v[42:45], v[154:157], v[192:195], v[42:45]
	v_mfma_f32_16x16x32_bf16 v[50:53], v[146:149], v[192:195], v[50:53]
	v_mfma_f32_16x16x32_bf16 v[34:37], v[146:149], v[200:203], v[34:37]
	v_mfma_f32_16x16x32_bf16 v[26:29], v[154:157], v[200:203], v[26:29]
	v_mfma_f32_16x16x32_bf16 v[10:13], v[154:157], v[208:211], v[10:13]
	v_mfma_f32_16x16x32_bf16 v[18:21], v[146:149], v[208:211], v[18:21]
	v_mfma_f32_16x16x32_bf16 v[62:65], v[150:153], v[182:185], v[62:65]
	v_mfma_f32_16x16x32_bf16 v[58:61], v[158:161], v[182:185], v[58:61]
	v_mfma_f32_16x16x32_bf16 v[42:45], v[158:161], v[196:199], v[42:45]
	v_mfma_f32_16x16x32_bf16 v[50:53], v[150:153], v[196:199], v[50:53]
	v_mfma_f32_16x16x32_bf16 v[34:37], v[150:153], v[204:207], v[34:37]
	v_mfma_f32_16x16x32_bf16 v[26:29], v[158:161], v[204:207], v[26:29]
	v_mfma_f32_16x16x32_bf16 v[10:13], v[158:161], v[212:215], v[10:13]
	v_mfma_f32_16x16x32_bf16 v[18:21], v[150:153], v[212:215], v[18:21]


	v_mfma_f32_16x16x32_bf16 v[54:57], v[162:165], v[178:181], v[54:57]
	v_mfma_f32_16x16x32_bf16 v[46:49], v[170:173], v[178:181], v[46:49]
	v_mfma_f32_16x16x32_bf16 v[30:33], v[170:173], v[192:195], v[30:33]
	v_mfma_f32_16x16x32_bf16 v[38:41], v[162:165], v[192:195], v[38:41]
	v_mfma_f32_16x16x32_bf16 v[22:25], v[162:165], v[200:203], v[22:25]
	v_mfma_f32_16x16x32_bf16 v[14:17], v[170:173], v[200:203], v[14:17]
	v_mfma_f32_16x16x32_bf16 v[2:5], v[170:173], v[208:211], v[2:5]
	v_mfma_f32_16x16x32_bf16 v[6:9], v[162:165], v[208:211], v[6:9]
	v_mfma_f32_16x16x32_bf16 v[54:57], v[166:169], v[182:185], v[54:57]
	v_mfma_f32_16x16x32_bf16 v[46:49], v[174:177], v[182:185], v[46:49]
	v_mfma_f32_16x16x32_bf16 v[30:33], v[174:177], v[196:199], v[30:33]
	v_mfma_f32_16x16x32_bf16 v[38:41], v[166:169], v[196:199], v[38:41]
	v_mfma_f32_16x16x32_bf16 v[22:25], v[166:169], v[204:207], v[22:25]
	v_mfma_f32_16x16x32_bf16 v[14:17], v[174:177], v[204:207], v[14:17]
	v_mfma_f32_16x16x32_bf16 v[2:5], v[174:177], v[212:215], v[2:5]
	v_mfma_f32_16x16x32_bf16 v[6:9], v[166:169], v[212:215], v[6:9]
	s_barrier
	s_setprio 0
	s_add_i32 s0, 0, 0x18000
	s_add_i32 s1, 0, 0x1c000
	v_add_u32_e32 v158, s0, v144
	v_add_u32_e32 v174, s1, v144
	ds_read_b128 v[146:149], v158
	ds_read_b128 v[150:153], v158 offset:1024
	ds_read_b128 v[154:157], v158 offset:2048
	ds_read_b128 v[158:161], v158 offset:3072
	ds_read_b128 v[162:165], v174
	ds_read_b128 v[166:169], v174 offset:1024
	ds_read_b128 v[170:173], v174 offset:2048
	ds_read_b128 v[174:177], v174 offset:3072
	s_add_u32 s30, s30, 0x80000
	s_addc_u32 s31, s31, 0
	s_mov_b32 m0, s41
	v_lshl_add_u64 v[220:221], s[30:31], 0, v[134:135]
	ds_read_b128 v[178:181], v145 offset:32768
	ds_read_b128 v[182:185], v145 offset:33792
	ds_read_b128 v[192:195], v145 offset:34816
	ds_read_b128 v[196:199], v145 offset:35840
	ds_read_b128 v[200:203], v145 offset:36864
	ds_read_b128 v[204:207], v145 offset:37888
	ds_read_b128 v[208:211], v145 offset:38912
	ds_read_b128 v[212:215], v145 offset:39936
	global_load_lds_dwordx4 v[220:221], off
	v_lshl_add_u64 v[220:221], s[30:31], 0, v[132:133]
	s_mov_b32 m0, s42
	s_nop 0
	global_load_lds_dwordx4 v[220:221], off
	s_waitcnt vmcnt(8)
	s_waitcnt lgkmcnt(0)
	s_setprio 1
	s_barrier

	v_mfma_f32_16x16x32_bf16 v[126:129], v[146:149], v[178:181], v[126:129]
	v_mfma_f32_16x16x32_bf16 v[122:125], v[154:157], v[178:181], v[122:125]
	v_mfma_f32_16x16x32_bf16 v[106:109], v[154:157], v[192:195], v[106:109]
	v_mfma_f32_16x16x32_bf16 v[114:117], v[146:149], v[192:195], v[114:117]
	v_mfma_f32_16x16x32_bf16 v[98:101], v[146:149], v[200:203], v[98:101]
	v_mfma_f32_16x16x32_bf16 v[90:93], v[154:157], v[200:203], v[90:93]
	v_mfma_f32_16x16x32_bf16 v[74:77], v[154:157], v[208:211], v[74:77]
	v_mfma_f32_16x16x32_bf16 v[82:85], v[146:149], v[208:211], v[82:85]
	v_mfma_f32_16x16x32_bf16 v[126:129], v[150:153], v[182:185], v[126:129]
	v_mfma_f32_16x16x32_bf16 v[122:125], v[158:161], v[182:185], v[122:125]
	v_mfma_f32_16x16x32_bf16 v[106:109], v[158:161], v[196:199], v[106:109]
	v_mfma_f32_16x16x32_bf16 v[114:117], v[150:153], v[196:199], v[114:117]
	v_mfma_f32_16x16x32_bf16 v[98:101], v[150:153], v[204:207], v[98:101]
	v_mfma_f32_16x16x32_bf16 v[90:93], v[158:161], v[204:207], v[90:93]
	v_mfma_f32_16x16x32_bf16 v[74:77], v[158:161], v[212:215], v[74:77]
	v_mfma_f32_16x16x32_bf16 v[82:85], v[150:153], v[212:215], v[82:85]


	v_mfma_f32_16x16x32_bf16 v[118:121], v[162:165], v[178:181], v[118:121]
	v_mfma_f32_16x16x32_bf16 v[110:113], v[170:173], v[178:181], v[110:113]
	v_mfma_f32_16x16x32_bf16 v[94:97], v[170:173], v[192:195], v[94:97]
	v_mfma_f32_16x16x32_bf16 v[102:105], v[162:165], v[192:195], v[102:105]
	v_mfma_f32_16x16x32_bf16 v[86:89], v[162:165], v[200:203], v[86:89]
	v_mfma_f32_16x16x32_bf16 v[78:81], v[170:173], v[200:203], v[78:81]
	v_mfma_f32_16x16x32_bf16 v[66:69], v[170:173], v[208:211], v[66:69]
	v_mfma_f32_16x16x32_bf16 v[70:73], v[162:165], v[208:211], v[70:73]
	v_mfma_f32_16x16x32_bf16 v[118:121], v[166:169], v[182:185], v[118:121]
	v_mfma_f32_16x16x32_bf16 v[110:113], v[174:177], v[182:185], v[110:113]
	v_mfma_f32_16x16x32_bf16 v[94:97], v[174:177], v[196:199], v[94:97]
	v_mfma_f32_16x16x32_bf16 v[102:105], v[166:169], v[196:199], v[102:105]
	v_mfma_f32_16x16x32_bf16 v[86:89], v[166:169], v[204:207], v[86:89]
	v_mfma_f32_16x16x32_bf16 v[78:81], v[174:177], v[204:207], v[78:81]
	v_mfma_f32_16x16x32_bf16 v[66:69], v[174:177], v[212:215], v[66:69]
	v_mfma_f32_16x16x32_bf16 v[70:73], v[166:169], v[212:215], v[70:73]
	s_barrier
	s_setprio 0
	s_add_i32 s0, s0, s39
	v_lshl_add_u64 v[140:141], v[140:141], 0, s[84:85]
	s_mov_b32 m0, s0
	ds_read_b128 v[178:181], v145 offset:49152
	ds_read_b128 v[182:185], v145 offset:50176
	ds_read_b128 v[192:195], v145 offset:51200
	ds_read_b128 v[196:199], v145 offset:52224
	ds_read_b128 v[200:203], v145 offset:53248
	ds_read_b128 v[204:207], v145 offset:54272
	ds_read_b128 v[208:211], v145 offset:55296
	ds_read_b128 v[212:215], v145 offset:56320
	global_load_lds_dwordx4 v[140:141], off
	s_add_i32 m0, s0, 0x2000
	s_add_u32 s28, s28, 0x80080
	v_lshl_add_u64 v[140:141], v[188:189], 0, s[84:85]
	s_addc_u32 s29, s29, 0
	s_add_i32 s0, s1, s39
	global_load_lds_dwordx4 v[140:141], off
	v_lshl_add_u64 v[140:141], s[28:29], 0, v[186:187]
	s_mov_b32 m0, s0
	s_nop 0
	global_load_lds_dwordx4 v[140:141], off
	v_lshl_add_u64 v[140:141], s[28:29], 0, v[130:131]
	s_add_i32 m0, s0, 0x2000
	s_nop 0
	global_load_lds_dwordx4 v[140:141], off
	v_lshl_add_u64 v[140:141], v[216:217], 0, s[84:85]
	s_mov_b32 m0, s43
	s_nop 0
	global_load_lds_dwordx4 v[140:141], off
	v_lshl_add_u64 v[140:141], v[218:219], 0, s[84:85]
	s_mov_b32 m0, s44
	s_nop 0
	global_load_lds_dwordx4 v[140:141], off
	s_waitcnt vmcnt(8)
	s_waitcnt lgkmcnt(0)
	s_setprio 1
	s_barrier

	v_mfma_f32_16x16x32_bf16 v[62:65], v[146:149], v[178:181], v[62:65]
	v_mfma_f32_16x16x32_bf16 v[58:61], v[154:157], v[178:181], v[58:61]
	v_mfma_f32_16x16x32_bf16 v[42:45], v[154:157], v[192:195], v[42:45]
	v_mfma_f32_16x16x32_bf16 v[50:53], v[146:149], v[192:195], v[50:53]
	v_mfma_f32_16x16x32_bf16 v[34:37], v[146:149], v[200:203], v[34:37]
	v_mfma_f32_16x16x32_bf16 v[26:29], v[154:157], v[200:203], v[26:29]
	v_mfma_f32_16x16x32_bf16 v[10:13], v[154:157], v[208:211], v[10:13]
	v_mfma_f32_16x16x32_bf16 v[18:21], v[146:149], v[208:211], v[18:21]
	v_mfma_f32_16x16x32_bf16 v[62:65], v[150:153], v[182:185], v[62:65]
	v_mfma_f32_16x16x32_bf16 v[58:61], v[158:161], v[182:185], v[58:61]
	v_mfma_f32_16x16x32_bf16 v[42:45], v[158:161], v[196:199], v[42:45]
	v_mfma_f32_16x16x32_bf16 v[50:53], v[150:153], v[196:199], v[50:53]
	v_mfma_f32_16x16x32_bf16 v[34:37], v[150:153], v[204:207], v[34:37]
	v_mfma_f32_16x16x32_bf16 v[26:29], v[158:161], v[204:207], v[26:29]
	v_mfma_f32_16x16x32_bf16 v[10:13], v[158:161], v[212:215], v[10:13]
	v_mfma_f32_16x16x32_bf16 v[18:21], v[150:153], v[212:215], v[18:21]


	v_mfma_f32_16x16x32_bf16 v[54:57], v[162:165], v[178:181], v[54:57]
	v_mfma_f32_16x16x32_bf16 v[46:49], v[170:173], v[178:181], v[46:49]
	v_mfma_f32_16x16x32_bf16 v[30:33], v[170:173], v[192:195], v[30:33]
	v_mfma_f32_16x16x32_bf16 v[38:41], v[162:165], v[192:195], v[38:41]
	v_mfma_f32_16x16x32_bf16 v[22:25], v[162:165], v[200:203], v[22:25]
	v_mfma_f32_16x16x32_bf16 v[14:17], v[170:173], v[200:203], v[14:17]
	v_mfma_f32_16x16x32_bf16 v[2:5], v[170:173], v[208:211], v[2:5]
	v_mfma_f32_16x16x32_bf16 v[6:9], v[162:165], v[208:211], v[6:9]
	v_mfma_f32_16x16x32_bf16 v[54:57], v[166:169], v[182:185], v[54:57]
	v_mfma_f32_16x16x32_bf16 v[46:49], v[174:177], v[182:185], v[46:49]
	v_mfma_f32_16x16x32_bf16 v[30:33], v[174:177], v[196:199], v[30:33]
	v_mfma_f32_16x16x32_bf16 v[38:41], v[166:169], v[196:199], v[38:41]
	v_mfma_f32_16x16x32_bf16 v[22:25], v[166:169], v[204:207], v[22:25]
	v_mfma_f32_16x16x32_bf16 v[14:17], v[174:177], v[204:207], v[14:17]
	v_mfma_f32_16x16x32_bf16 v[2:5], v[174:177], v[212:215], v[2:5]
	v_mfma_f32_16x16x32_bf16 v[6:9], v[166:169], v[212:215], v[6:9]
	s_barrier
	s_setprio 0
	s_add_i32 s55, s55, 2
	s_add_u32 s26, s26, 0x100
	s_addc_u32 s27, s27, 0
	s_add_u32 s53, s53, 0x100
	s_addc_u32 s54, s54, 0
	s_cmp_gt_u32 s55, 29
	s_cbranch_scc0 .LBB0_443
	s_and_b64 vcc, exec, s[14:15]
	s_cbranch_vccz .LBB0_446
	s_barrier

.LBB0_1126:
	s_add_u32 s0, s28, 0xfff80080
	s_addc_u32 s1, s29, -1
	s_add_i32 s54, 0, 0x10000
	s_cmp_eq_u32 s53, 28
	s_cselect_b32 s35, s19, s1
	s_cselect_b32 s34, s25, s0
	s_cselect_b32 s31, s17, s52
	s_cselect_b32 s30, s27, s51
	s_add_i32 s55, 0, 0x14000
	v_add_u32_e32 v126, s54, v237
	v_add_u32_e32 v158, s55, v237
	ds_read_b128 v[90:93], v126
	ds_read_b128 v[102:105], v126 offset:1024
	ds_read_b128 v[114:117], v126 offset:2048
	ds_read_b128 v[126:129], v126 offset:3072
	ds_read_b128 v[138:141], v158
	ds_read_b128 v[142:145], v158 offset:1024
	ds_read_b128 v[154:157], v158 offset:2048
	ds_read_b128 v[158:161], v158 offset:3072
	v_lshl_add_u64 v[188:189], s[28:29], 0, v[198:199]
	s_add_i32 m0, s40, 0xc000
	ds_read_b128 v[162:165], v238
	ds_read_b128 v[166:169], v238 offset:1024
	ds_read_b128 v[170:173], v238 offset:2048
	ds_read_b128 v[174:177], v238 offset:3072
	ds_read_b128 v[178:181], v238 offset:4096
	ds_read_b128 v[182:185], v238 offset:5120
	ds_read_b128 v[202:205], v238 offset:6144
	ds_read_b128 v[206:209], v238 offset:7168
	global_load_lds_dwordx4 v[188:189], off
	v_lshl_add_u64 v[188:189], s[28:29], 0, v[200:201]
	s_add_i32 m0, s40, 0xe000
	s_nop 0
	global_load_lds_dwordx4 v[188:189], off
	s_waitcnt vmcnt(8)
	s_waitcnt lgkmcnt(0)
	s_setprio 1
	s_barrier

	v_mfma_f32_16x16x32_bf16 v[150:153], v[90:93], v[162:165], v[150:153]
	v_mfma_f32_16x16x32_bf16 v[146:149], v[114:117], v[162:165], v[146:149]
	v_mfma_f32_16x16x32_bf16 v[118:121], v[114:117], v[170:173], v[118:121]
	v_mfma_f32_16x16x32_bf16 v[122:125], v[90:93], v[170:173], v[122:125]
	v_mfma_f32_16x16x32_bf16 v[98:101], v[90:93], v[178:181], v[98:101]
	v_mfma_f32_16x16x32_bf16 v[94:97], v[114:117], v[178:181], v[94:97]
	v_mfma_f32_16x16x32_bf16 v[74:77], v[114:117], v[202:205], v[74:77]
	v_mfma_f32_16x16x32_bf16 v[78:81], v[90:93], v[202:205], v[78:81]
	v_mfma_f32_16x16x32_bf16 v[150:153], v[102:105], v[166:169], v[150:153]
	v_mfma_f32_16x16x32_bf16 v[146:149], v[126:129], v[166:169], v[146:149]
	v_mfma_f32_16x16x32_bf16 v[118:121], v[126:129], v[174:177], v[118:121]
	v_mfma_f32_16x16x32_bf16 v[122:125], v[102:105], v[174:177], v[122:125]
	v_mfma_f32_16x16x32_bf16 v[98:101], v[102:105], v[182:185], v[98:101]
	v_mfma_f32_16x16x32_bf16 v[94:97], v[126:129], v[182:185], v[94:97]
	v_mfma_f32_16x16x32_bf16 v[74:77], v[126:129], v[206:209], v[74:77]
	v_mfma_f32_16x16x32_bf16 v[78:81], v[102:105], v[206:209], v[78:81]


	v_mfma_f32_16x16x32_bf16 v[134:137], v[138:141], v[162:165], v[134:137]
	v_mfma_f32_16x16x32_bf16 v[130:133], v[154:157], v[162:165], v[130:133]
	v_mfma_f32_16x16x32_bf16 v[106:109], v[154:157], v[170:173], v[106:109]
	v_mfma_f32_16x16x32_bf16 v[110:113], v[138:141], v[170:173], v[110:113]
	v_mfma_f32_16x16x32_bf16 v[86:89], v[138:141], v[178:181], v[86:89]
	v_mfma_f32_16x16x32_bf16 v[82:85], v[154:157], v[178:181], v[82:85]
	v_mfma_f32_16x16x32_bf16 v[66:69], v[154:157], v[202:205], v[66:69]
	v_mfma_f32_16x16x32_bf16 v[70:73], v[138:141], v[202:205], v[70:73]
	v_mfma_f32_16x16x32_bf16 v[134:137], v[142:145], v[166:169], v[134:137]
	v_mfma_f32_16x16x32_bf16 v[130:133], v[158:161], v[166:169], v[130:133]
	v_mfma_f32_16x16x32_bf16 v[106:109], v[158:161], v[174:177], v[106:109]
	v_mfma_f32_16x16x32_bf16 v[110:113], v[142:145], v[174:177], v[110:113]
	v_mfma_f32_16x16x32_bf16 v[86:89], v[142:145], v[182:185], v[86:89]
	v_mfma_f32_16x16x32_bf16 v[82:85], v[158:161], v[182:185], v[82:85]
	v_mfma_f32_16x16x32_bf16 v[66:69], v[158:161], v[206:209], v[66:69]
	v_mfma_f32_16x16x32_bf16 v[70:73], v[142:145], v[206:209], v[70:73]
	s_barrier
	s_setprio 0
	s_add_i32 s0, s54, s39
	v_lshl_add_u64 v[188:189], s[30:31], 0, v[186:187]
	s_mov_b32 m0, s0
	ds_read_b128 v[162:165], v238 offset:16384
	ds_read_b128 v[166:169], v238 offset:17408
	ds_read_b128 v[170:173], v238 offset:18432
	ds_read_b128 v[174:177], v238 offset:19456
	ds_read_b128 v[178:181], v238 offset:20480
	ds_read_b128 v[182:185], v238 offset:21504
	ds_read_b128 v[202:205], v238 offset:22528
	ds_read_b128 v[206:209], v238 offset:23552
	global_load_lds_dwordx4 v[188:189], off
	s_add_i32 m0, s0, 0x2000
	s_add_u32 s0, s30, 0x80000
	v_lshl_add_u64 v[210:211], s[30:31], 0, v[196:197]
	s_addc_u32 s1, s31, 0
	s_add_i32 s54, s55, s39
	global_load_lds_dwordx4 v[210:211], off
	v_lshl_add_u64 v[212:213], s[0:1], 0, v[186:187]
	s_mov_b32 m0, s54
	v_lshl_add_u64 v[214:215], s[34:35], 0, v[194:195]
	global_load_lds_dwordx4 v[212:213], off
	v_lshl_add_u64 v[212:213], s[0:1], 0, v[196:197]
	s_add_i32 m0, s54, 0x2000
	s_nop 0
	global_load_lds_dwordx4 v[212:213], off
	v_lshl_add_u64 v[212:213], s[34:35], 0, v[192:193]
	s_mov_b32 m0, s40
	s_nop 0
	global_load_lds_dwordx4 v[212:213], off
	s_mov_b32 m0, s41
	s_nop 0
	global_load_lds_dwordx4 v[214:215], off
	s_waitcnt vmcnt(8)
	s_waitcnt lgkmcnt(0)
	s_setprio 1
	s_barrier

	v_mfma_f32_16x16x32_bf16 v[62:65], v[90:93], v[162:165], v[62:65]
	v_mfma_f32_16x16x32_bf16 v[58:61], v[114:117], v[162:165], v[58:61]
	v_mfma_f32_16x16x32_bf16 v[42:45], v[114:117], v[170:173], v[42:45]
	v_mfma_f32_16x16x32_bf16 v[46:49], v[90:93], v[170:173], v[46:49]
	v_mfma_f32_16x16x32_bf16 v[30:33], v[90:93], v[178:181], v[30:33]
	v_mfma_f32_16x16x32_bf16 v[26:29], v[114:117], v[178:181], v[26:29]
	v_mfma_f32_16x16x32_bf16 v[10:13], v[114:117], v[202:205], v[10:13]
	v_mfma_f32_16x16x32_bf16 v[14:17], v[90:93], v[202:205], v[14:17]
	v_mfma_f32_16x16x32_bf16 v[62:65], v[102:105], v[166:169], v[62:65]
	v_mfma_f32_16x16x32_bf16 v[58:61], v[126:129], v[166:169], v[58:61]
	v_mfma_f32_16x16x32_bf16 v[42:45], v[126:129], v[174:177], v[42:45]
	v_mfma_f32_16x16x32_bf16 v[46:49], v[102:105], v[174:177], v[46:49]
	v_mfma_f32_16x16x32_bf16 v[30:33], v[102:105], v[182:185], v[30:33]
	v_mfma_f32_16x16x32_bf16 v[26:29], v[126:129], v[182:185], v[26:29]
	v_mfma_f32_16x16x32_bf16 v[10:13], v[126:129], v[206:209], v[10:13]
	v_mfma_f32_16x16x32_bf16 v[14:17], v[102:105], v[206:209], v[14:17]


	v_mfma_f32_16x16x32_bf16 v[54:57], v[138:141], v[162:165], v[54:57]
	v_mfma_f32_16x16x32_bf16 v[50:53], v[154:157], v[162:165], v[50:53]
	v_mfma_f32_16x16x32_bf16 v[34:37], v[154:157], v[170:173], v[34:37]
	v_mfma_f32_16x16x32_bf16 v[38:41], v[138:141], v[170:173], v[38:41]
	v_mfma_f32_16x16x32_bf16 v[22:25], v[138:141], v[178:181], v[22:25]
	v_mfma_f32_16x16x32_bf16 v[18:21], v[154:157], v[178:181], v[18:21]
	v_mfma_f32_16x16x32_bf16 v[2:5], v[154:157], v[202:205], v[2:5]
	v_mfma_f32_16x16x32_bf16 v[6:9], v[138:141], v[202:205], v[6:9]
	v_mfma_f32_16x16x32_bf16 v[54:57], v[142:145], v[166:169], v[54:57]
	v_mfma_f32_16x16x32_bf16 v[50:53], v[158:161], v[166:169], v[50:53]
	v_mfma_f32_16x16x32_bf16 v[34:37], v[158:161], v[174:177], v[34:37]
	v_mfma_f32_16x16x32_bf16 v[38:41], v[142:145], v[174:177], v[38:41]
	v_mfma_f32_16x16x32_bf16 v[22:25], v[142:145], v[182:185], v[22:25]
	v_mfma_f32_16x16x32_bf16 v[18:21], v[158:161], v[182:185], v[18:21]
	v_mfma_f32_16x16x32_bf16 v[2:5], v[158:161], v[206:209], v[2:5]
	v_mfma_f32_16x16x32_bf16 v[6:9], v[142:145], v[206:209], v[6:9]
	s_barrier
	s_setprio 0
	s_add_i32 s54, 0, 0x18000
	s_add_i32 s55, 0, 0x1c000
	v_add_u32_e32 v126, s54, v237
	v_add_u32_e32 v158, s55, v237
	ds_read_b128 v[90:93], v126
	ds_read_b128 v[102:105], v126 offset:1024
	ds_read_b128 v[114:117], v126 offset:2048
	ds_read_b128 v[126:129], v126 offset:3072
	ds_read_b128 v[138:141], v158
	ds_read_b128 v[142:145], v158 offset:1024
	ds_read_b128 v[154:157], v158 offset:2048
	ds_read_b128 v[158:161], v158 offset:3072
	s_add_u32 s0, s34, 0x80000
	s_addc_u32 s1, s35, 0
	s_mov_b32 m0, s42
	v_lshl_add_u64 v[216:217], s[0:1], 0, v[192:193]
	ds_read_b128 v[162:165], v238 offset:32768
	ds_read_b128 v[166:169], v238 offset:33792
	ds_read_b128 v[170:173], v238 offset:34816
	ds_read_b128 v[174:177], v238 offset:35840
	ds_read_b128 v[178:181], v238 offset:36864
	ds_read_b128 v[182:185], v238 offset:37888
	ds_read_b128 v[202:205], v238 offset:38912
	ds_read_b128 v[206:209], v238 offset:39936
	global_load_lds_dwordx4 v[216:217], off
	v_lshl_add_u64 v[216:217], s[0:1], 0, v[194:195]
	s_mov_b32 m0, s43
	s_nop 0
	global_load_lds_dwordx4 v[216:217], off
	s_waitcnt vmcnt(8)
	s_waitcnt lgkmcnt(0)
	s_setprio 1
	s_barrier

	v_mfma_f32_16x16x32_bf16 v[150:153], v[90:93], v[162:165], v[150:153]
	v_mfma_f32_16x16x32_bf16 v[146:149], v[114:117], v[162:165], v[146:149]
	v_mfma_f32_16x16x32_bf16 v[118:121], v[114:117], v[170:173], v[118:121]
	v_mfma_f32_16x16x32_bf16 v[122:125], v[90:93], v[170:173], v[122:125]
	v_mfma_f32_16x16x32_bf16 v[98:101], v[90:93], v[178:181], v[98:101]
	v_mfma_f32_16x16x32_bf16 v[94:97], v[114:117], v[178:181], v[94:97]
	v_mfma_f32_16x16x32_bf16 v[74:77], v[114:117], v[202:205], v[74:77]
	v_mfma_f32_16x16x32_bf16 v[78:81], v[90:93], v[202:205], v[78:81]
	v_mfma_f32_16x16x32_bf16 v[150:153], v[102:105], v[166:169], v[150:153]
	v_mfma_f32_16x16x32_bf16 v[146:149], v[126:129], v[166:169], v[146:149]
	v_mfma_f32_16x16x32_bf16 v[118:121], v[126:129], v[174:177], v[118:121]
	v_mfma_f32_16x16x32_bf16 v[122:125], v[102:105], v[174:177], v[122:125]
	v_mfma_f32_16x16x32_bf16 v[98:101], v[102:105], v[182:185], v[98:101]
	v_mfma_f32_16x16x32_bf16 v[94:97], v[126:129], v[182:185], v[94:97]
	v_mfma_f32_16x16x32_bf16 v[74:77], v[126:129], v[206:209], v[74:77]
	v_mfma_f32_16x16x32_bf16 v[78:81], v[102:105], v[206:209], v[78:81]


	v_mfma_f32_16x16x32_bf16 v[134:137], v[138:141], v[162:165], v[134:137]
	v_mfma_f32_16x16x32_bf16 v[130:133], v[154:157], v[162:165], v[130:133]
	v_mfma_f32_16x16x32_bf16 v[106:109], v[154:157], v[170:173], v[106:109]
	v_mfma_f32_16x16x32_bf16 v[110:113], v[138:141], v[170:173], v[110:113]
	v_mfma_f32_16x16x32_bf16 v[86:89], v[138:141], v[178:181], v[86:89]
	v_mfma_f32_16x16x32_bf16 v[82:85], v[154:157], v[178:181], v[82:85]
	v_mfma_f32_16x16x32_bf16 v[66:69], v[154:157], v[202:205], v[66:69]
	v_mfma_f32_16x16x32_bf16 v[70:73], v[138:141], v[202:205], v[70:73]
	v_mfma_f32_16x16x32_bf16 v[134:137], v[142:145], v[166:169], v[134:137]
	v_mfma_f32_16x16x32_bf16 v[130:133], v[158:161], v[166:169], v[130:133]
	v_mfma_f32_16x16x32_bf16 v[106:109], v[158:161], v[174:177], v[106:109]
	v_mfma_f32_16x16x32_bf16 v[110:113], v[142:145], v[174:177], v[110:113]
	v_mfma_f32_16x16x32_bf16 v[86:89], v[142:145], v[182:185], v[86:89]
	v_mfma_f32_16x16x32_bf16 v[82:85], v[158:161], v[182:185], v[82:85]
	v_mfma_f32_16x16x32_bf16 v[66:69], v[158:161], v[206:209], v[66:69]
	v_mfma_f32_16x16x32_bf16 v[70:73], v[142:145], v[206:209], v[70:73]
	s_barrier
	s_setprio 0
	s_add_i32 s0, s54, s39
	v_lshl_add_u64 v[188:189], v[188:189], 0, s[84:85]
	s_mov_b32 m0, s0
	ds_read_b128 v[162:165], v238 offset:49152
	ds_read_b128 v[166:169], v238 offset:50176
	ds_read_b128 v[170:173], v238 offset:51200
	ds_read_b128 v[174:177], v238 offset:52224
	ds_read_b128 v[178:181], v238 offset:53248
	ds_read_b128 v[182:185], v238 offset:54272
	ds_read_b128 v[202:205], v238 offset:55296
	ds_read_b128 v[206:209], v238 offset:56320
	global_load_lds_dwordx4 v[188:189], off
	s_add_i32 m0, s0, 0x2000
	s_add_u32 s0, s30, 0x80080
	v_lshl_add_u64 v[188:189], v[210:211], 0, s[84:85]
	s_addc_u32 s1, s31, 0
	s_add_i32 s30, s55, s39
	global_load_lds_dwordx4 v[188:189], off
	v_lshl_add_u64 v[188:189], s[0:1], 0, v[186:187]
	s_mov_b32 m0, s30
	s_nop 0
	global_load_lds_dwordx4 v[188:189], off
	v_lshl_add_u64 v[188:189], s[0:1], 0, v[196:197]
	s_add_i32 m0, s30, 0x2000
	s_nop 0
	global_load_lds_dwordx4 v[188:189], off
	v_lshl_add_u64 v[188:189], v[212:213], 0, s[84:85]
	s_mov_b32 m0, s47
	s_nop 0
	global_load_lds_dwordx4 v[188:189], off
	v_lshl_add_u64 v[188:189], v[214:215], 0, s[84:85]
	s_mov_b32 m0, s48
	s_nop 0
	global_load_lds_dwordx4 v[188:189], off
	s_waitcnt vmcnt(8)
	s_waitcnt lgkmcnt(0)
	s_setprio 1
	s_barrier

	v_mfma_f32_16x16x32_bf16 v[62:65], v[90:93], v[162:165], v[62:65]
	v_mfma_f32_16x16x32_bf16 v[58:61], v[114:117], v[162:165], v[58:61]
	v_mfma_f32_16x16x32_bf16 v[42:45], v[114:117], v[170:173], v[42:45]
	v_mfma_f32_16x16x32_bf16 v[46:49], v[90:93], v[170:173], v[46:49]
	v_mfma_f32_16x16x32_bf16 v[30:33], v[90:93], v[178:181], v[30:33]
	v_mfma_f32_16x16x32_bf16 v[26:29], v[114:117], v[178:181], v[26:29]
	v_mfma_f32_16x16x32_bf16 v[10:13], v[114:117], v[202:205], v[10:13]
	v_mfma_f32_16x16x32_bf16 v[14:17], v[90:93], v[202:205], v[14:17]
	v_mfma_f32_16x16x32_bf16 v[62:65], v[102:105], v[166:169], v[62:65]
	v_mfma_f32_16x16x32_bf16 v[58:61], v[126:129], v[166:169], v[58:61]
	v_mfma_f32_16x16x32_bf16 v[42:45], v[126:129], v[174:177], v[42:45]
	v_mfma_f32_16x16x32_bf16 v[46:49], v[102:105], v[174:177], v[46:49]
	v_mfma_f32_16x16x32_bf16 v[30:33], v[102:105], v[182:185], v[30:33]
	v_mfma_f32_16x16x32_bf16 v[26:29], v[126:129], v[182:185], v[26:29]
	v_mfma_f32_16x16x32_bf16 v[10:13], v[126:129], v[206:209], v[10:13]
	v_mfma_f32_16x16x32_bf16 v[14:17], v[102:105], v[206:209], v[14:17]


	v_mfma_f32_16x16x32_bf16 v[54:57], v[138:141], v[162:165], v[54:57]
	v_mfma_f32_16x16x32_bf16 v[50:53], v[154:157], v[162:165], v[50:53]
	v_mfma_f32_16x16x32_bf16 v[34:37], v[154:157], v[170:173], v[34:37]
	v_mfma_f32_16x16x32_bf16 v[38:41], v[138:141], v[170:173], v[38:41]
	v_mfma_f32_16x16x32_bf16 v[22:25], v[138:141], v[178:181], v[22:25]
	v_mfma_f32_16x16x32_bf16 v[18:21], v[154:157], v[178:181], v[18:21]
	v_mfma_f32_16x16x32_bf16 v[2:5], v[154:157], v[202:205], v[2:5]
	v_mfma_f32_16x16x32_bf16 v[6:9], v[138:141], v[202:205], v[6:9]
	v_mfma_f32_16x16x32_bf16 v[54:57], v[142:145], v[166:169], v[54:57]
	v_mfma_f32_16x16x32_bf16 v[50:53], v[158:161], v[166:169], v[50:53]
	v_mfma_f32_16x16x32_bf16 v[34:37], v[158:161], v[174:177], v[34:37]
	v_mfma_f32_16x16x32_bf16 v[38:41], v[142:145], v[174:177], v[38:41]
	v_mfma_f32_16x16x32_bf16 v[22:25], v[142:145], v[182:185], v[22:25]
	v_mfma_f32_16x16x32_bf16 v[18:21], v[158:161], v[182:185], v[18:21]
	v_mfma_f32_16x16x32_bf16 v[2:5], v[158:161], v[206:209], v[2:5]
	v_mfma_f32_16x16x32_bf16 v[6:9], v[142:145], v[206:209], v[6:9]
	s_barrier
	s_setprio 0
	s_add_i32 s53, s53, 2
	s_add_u32 s28, s28, 0x100
	s_addc_u32 s29, s29, 0
	s_add_u32 s51, s51, 0x100
	s_addc_u32 s52, s52, 0
	s_cmp_gt_u32 s53, 29
	s_cbranch_scc0 .LBB0_1126
	s_and_b64 vcc, exec, s[14:15]
	s_cbranch_vccz .LBB0_1129
	s_barrier
